# K-loops: first load interval's ds_reads issued at the top of the loop body ahead of the DMA address SALU (DOWN: also ahead of the loop header block)
# baseline (speedup 1.0000x reference)
; #define PG8_STAGE(bufoff, gbase, voff) do { _Pragma("unroll") for (int _i = 0; _i < 2; ++_i) \
;         __builtin_amdgcn_global_load_lds((const unsigned*)((const char*)(gbase) + (voff)[_i]), (PG8_LAS unsigned*)(lds + (bufoff) + ldsw + _i * 8192), 16, 0, 0); } while (0)
; #define PG8_LDA(dst, b, h) do { _Pragma("unroll") for (int m = 0; m < 4; ++m) _Pragma("unroll") for (int k = 0; k < 2; ++k) dst[m][k] = *(const PG8_LAS bf16x8*)(lds + PG8_SA(b, h) + aoff + m * 2048 + k * 1024); } while (0)
; #define PG8_LDB(dst, b, h) do { _Pragma("unroll") for (int n = 0; n < 2; ++n) _Pragma("unroll") for (int k = 0; k < 2; ++k) dst[n][k] = *(const PG8_LAS bf16x8*)(lds + PG8_SB(b, h) + boff + n * 2048 + k * 1024); } while (0)
; #define PG8_MMA(ai, bj, At, Bt) do { __builtin_amdgcn_s_setprio(1); _Pragma("unroll") for (int m = 0; m < 4; ++m) _Pragma("unroll") for (int n = 0; n < 2; ++n) _Pragma("unroll") for (int k = 0; k < 2; ++k) \
;         acc[ai][bj][m][n] = __builtin_amdgcn_mfma_f32_16x16x32_bf16(Bt[n][k], At[m][k], acc[ai][bj][m][n], 0, 0, 0); __builtin_amdgcn_s_setprio(0); } while (0)
; #define PG8_WAIT_V(n) asm volatile("s_waitcnt vmcnt(" #n ")" ::: "memory")
; #define PG8_WAIT_L(n) asm volatile("s_waitcnt lgkmcnt(" #n ")" ::: "memory")
; #define PG8_BAR __builtin_amdgcn_s_barrier()
; #define PG8_SCHED __builtin_amdgcn_sched_barrier(0)
;     ...
;             const bool last = (t == nt - 2);
;             const char* a1 = cA + (ptrdiff_t)(t + 1) * kstepA;
;             const char* a2 = last ? nA : cA + (ptrdiff_t)(t + 2) * kstepA; const char* b2 = last ? nB : cB + (ptrdiff_t)(t + 2) * kstep;
;             const char* a3 = a2 + kstepA; const char* b3 = b2 + kstep;
;             if (last && has_next) S.a_ready(nxt);
;             if constexpr (SP2) {
;             PG8_LDB(B0, 0, 0); PG8_LDB(B1, 0, 1); PG8_SCHED; PG8_LDA(At, 0, 0); PG8_STAGE(PG8_SA(1, 1), a1 + hstepA, voffA);
;             PG8_WAIT_V(8); PG8_WAIT_L(0); PG8_BAR; PG8_MMA(0, 0, At, B0); PG8_MMA(0, 1, At, B1); PG8_BAR; PG8_SCHED;
;             PG8_LDA(At, 0, 1); PG8_STAGE(PG8_SB(0, 0), b2, voffB); PG8_STAGE(PG8_SB(0, 1), b2 + hstepB, voffB); PG8_STAGE(PG8_SA(0, 0), a2, voffA);
;             PG8_WAIT_V(8); PG8_WAIT_L(0); PG8_BAR; PG8_MMA(1, 0, At, B0); PG8_MMA(1, 1, At, B1); PG8_BAR; PG8_SCHED;
.LBB0_328:
	s_add_i32 s65, 0, 0x10000
	s_add_i32 s66, 0, 0x14000
	v_add_u32_e32 v22, s65, v182
	v_add_u32_e32 v54, s66, v182
	ds_read_b128 v[10:13], v22
	ds_read_b128 v[14:17], v22 offset:1024
	ds_read_b128 v[18:21], v22 offset:2048
	ds_read_b128 v[22:25], v22 offset:3072
	ds_read_b128 v[26:29], v54
	ds_read_b128 v[38:41], v54 offset:1024
	ds_read_b128 v[50:53], v54 offset:2048
	ds_read_b128 v[54:57], v54 offset:3072
	ds_read_b128 v[172:175], v183
	ds_read_b128 v[176:179], v183 offset:1024
	ds_read_b128 v[184:187], v183 offset:2048
	ds_read_b128 v[188:191], v183 offset:3072
	ds_read_b128 v[192:195], v183 offset:4096
	ds_read_b128 v[196:199], v183 offset:5120
	ds_read_b128 v[200:203], v183 offset:6144
	ds_read_b128 v[204:207], v183 offset:7168
	s_add_i32 m0, s51, 0xc000
	s_add_u32 s100, s6, 0x4000
	s_addc_u32 s101, s7, 0
	s_cmp_eq_u32 vcc_lo, 28
	s_cselect_b32 s90, s54, s100
	s_cselect_b32 s91, s29, s101
	s_cselect_b32 s88, s55, s56
	s_cselect_b32 s89, s31, s57
	s_add_u32 s86, s90, 0x8000
	s_addc_u32 s87, s91, 0
	global_load_lds_dwordx4 v168, s[6:7]
	s_add_i32 m0, s51, 0xe000
	s_nop 0
	global_load_lds_dwordx4 v170, s[6:7]
	s_waitcnt vmcnt(8)
	s_waitcnt lgkmcnt(0)
	s_barrier
	s_setprio 1
	s_waitcnt lgkmcnt(0)
	v_mfma_f32_16x16x32_bf16 v[158:161], v[10:13], v[172:175], v[158:161]
	v_mfma_f32_16x16x32_bf16 v[158:161], v[14:17], v[176:179], v[158:161]
	v_mfma_f32_16x16x32_bf16 v[154:157], v[22:25], v[176:179], v[154:157]
	v_mfma_f32_16x16x32_bf16 v[154:157], v[18:21], v[172:175], v[154:157]
	v_mfma_f32_16x16x32_bf16 v[138:141], v[18:21], v[184:187], v[138:141]
	v_mfma_f32_16x16x32_bf16 v[138:141], v[22:25], v[188:191], v[138:141]
	v_mfma_f32_16x16x32_bf16 v[142:145], v[14:17], v[188:191], v[142:145]
	v_mfma_f32_16x16x32_bf16 v[142:145], v[10:13], v[184:187], v[142:145]
	v_mfma_f32_16x16x32_bf16 v[126:129], v[10:13], v[192:195], v[126:129]
	v_mfma_f32_16x16x32_bf16 v[126:129], v[14:17], v[196:199], v[126:129]
	v_mfma_f32_16x16x32_bf16 v[122:125], v[22:25], v[196:199], v[122:125]
	v_mfma_f32_16x16x32_bf16 v[122:125], v[18:21], v[192:195], v[122:125]
	v_mfma_f32_16x16x32_bf16 v[106:109], v[18:21], v[200:203], v[106:109]
	v_mfma_f32_16x16x32_bf16 v[106:109], v[22:25], v[204:207], v[106:109]
	v_mfma_f32_16x16x32_bf16 v[110:113], v[14:17], v[204:207], v[110:113]
	v_mfma_f32_16x16x32_bf16 v[110:113], v[10:13], v[200:203], v[110:113]
	s_setprio 0
	s_setprio 1
	v_mfma_f32_16x16x32_bf16 v[150:153], v[26:29], v[172:175], v[150:153]
	v_mfma_f32_16x16x32_bf16 v[150:153], v[38:41], v[176:179], v[150:153]
	v_mfma_f32_16x16x32_bf16 v[146:149], v[54:57], v[176:179], v[146:149]
	v_mfma_f32_16x16x32_bf16 v[146:149], v[50:53], v[172:175], v[146:149]
	v_mfma_f32_16x16x32_bf16 v[130:133], v[50:53], v[184:187], v[130:133]
	v_mfma_f32_16x16x32_bf16 v[130:133], v[54:57], v[188:191], v[130:133]
	v_mfma_f32_16x16x32_bf16 v[134:137], v[38:41], v[188:191], v[134:137]
	v_mfma_f32_16x16x32_bf16 v[134:137], v[26:29], v[184:187], v[134:137]
	v_mfma_f32_16x16x32_bf16 v[118:121], v[26:29], v[192:195], v[118:121]
	v_mfma_f32_16x16x32_bf16 v[118:121], v[38:41], v[196:199], v[118:121]
	v_mfma_f32_16x16x32_bf16 v[114:117], v[54:57], v[196:199], v[114:117]
	v_mfma_f32_16x16x32_bf16 v[114:117], v[50:53], v[192:195], v[114:117]
	v_mfma_f32_16x16x32_bf16 v[98:101], v[50:53], v[200:203], v[98:101]
	v_mfma_f32_16x16x32_bf16 v[98:101], v[54:57], v[204:207], v[98:101]
	v_mfma_f32_16x16x32_bf16 v[102:105], v[38:41], v[204:207], v[102:105]
	v_mfma_f32_16x16x32_bf16 v[102:105], v[26:29], v[200:203], v[102:105]
	s_setprio 0
	s_barrier
	s_add_i32 s65, s65, s2
	s_mov_b32 m0, s65
	ds_read_b128 v[172:175], v183 offset:16384
	ds_read_b128 v[176:179], v183 offset:17408
	ds_read_b128 v[184:187], v183 offset:18432
	ds_read_b128 v[188:191], v183 offset:19456
	ds_read_b128 v[192:195], v183 offset:20480
	ds_read_b128 v[196:199], v183 offset:21504
	ds_read_b128 v[200:203], v183 offset:22528
	ds_read_b128 v[204:207], v183 offset:23552
	global_load_lds_dwordx4 v0, s[88:89]
	s_add_i32 m0, s65, 0x2000
	s_add_u32 s96, s88, 0x4000
	s_addc_u32 s97, s89, 0
	s_add_i32 s65, s66, s2
	global_load_lds_dwordx4 v162, s[88:89]
	s_mov_b32 m0, s65
	s_nop 0
	global_load_lds_dwordx4 v0, s[96:97]
	s_add_i32 m0, s65, 0x2000
	s_nop 0
	global_load_lds_dwordx4 v162, s[96:97]
	s_mov_b32 m0, s51
	s_nop 0
	global_load_lds_dwordx4 v166, s[90:91]
	s_mov_b32 m0, s92
	s_nop 0
	global_load_lds_dwordx4 v164, s[90:91]
	s_waitcnt vmcnt(8)
	s_waitcnt lgkmcnt(0)
	s_barrier
	s_setprio 1
	s_waitcnt lgkmcnt(0)
	v_mfma_f32_16x16x32_bf16 v[94:97], v[10:13], v[172:175], v[94:97]
	v_mfma_f32_16x16x32_bf16 v[94:97], v[14:17], v[176:179], v[94:97]
	v_mfma_f32_16x16x32_bf16 v[90:93], v[18:21], v[172:175], v[90:93]
	v_mfma_f32_16x16x32_bf16 v[90:93], v[22:25], v[176:179], v[90:93]
	v_mfma_f32_16x16x32_bf16 v[78:81], v[10:13], v[184:187], v[78:81]
	v_mfma_f32_16x16x32_bf16 v[78:81], v[14:17], v[188:191], v[78:81]
	v_mfma_f32_16x16x32_bf16 v[74:77], v[18:21], v[184:187], v[74:77]
	v_mfma_f32_16x16x32_bf16 v[74:77], v[22:25], v[188:191], v[74:77]
	v_mfma_f32_16x16x32_bf16 v[62:65], v[10:13], v[192:195], v[62:65]
	v_mfma_f32_16x16x32_bf16 v[62:65], v[14:17], v[196:199], v[62:65]
	v_mfma_f32_16x16x32_bf16 v[58:61], v[18:21], v[192:195], v[58:61]
	v_mfma_f32_16x16x32_bf16 v[58:61], v[22:25], v[196:199], v[58:61]
	v_mfma_f32_16x16x32_bf16 v[10:13], v[10:13], v[200:203], v[34:37]
	v_mfma_f32_16x16x32_bf16 v[10:13], v[14:17], v[204:207], v[10:13]
	v_mfma_f32_16x16x32_bf16 v[14:17], v[18:21], v[200:203], v[30:33]
	v_mfma_f32_16x16x32_bf16 v[14:17], v[22:25], v[204:207], v[14:17]
	s_setprio 0
	s_setprio 1
	v_mfma_f32_16x16x32_bf16 v[30:33], v[26:29], v[184:187], v[70:73]
	v_mfma_f32_16x16x32_bf16 v[70:73], v[38:41], v[188:191], v[30:33]
	v_mfma_f32_16x16x32_bf16 v[30:33], v[50:53], v[184:187], v[66:69]
	v_mfma_f32_16x16x32_bf16 v[66:69], v[54:57], v[188:191], v[30:33]
	v_mfma_f32_16x16x32_bf16 v[30:33], v[26:29], v[192:195], v[46:49]
	v_mfma_f32_16x16x32_bf16 v[46:49], v[38:41], v[196:199], v[30:33]
	v_mfma_f32_16x16x32_bf16 v[30:33], v[50:53], v[192:195], v[42:45]
	v_mfma_f32_16x16x32_bf16 v[42:45], v[54:57], v[196:199], v[30:33]
	v_mfma_f32_16x16x32_bf16 v[6:9], v[26:29], v[200:203], v[6:9]
	v_mfma_f32_16x16x32_bf16 v[6:9], v[38:41], v[204:207], v[6:9]
	v_mfma_f32_16x16x32_bf16 v[2:5], v[50:53], v[200:203], v[2:5]
	v_mfma_f32_16x16x32_bf16 v[2:5], v[54:57], v[204:207], v[2:5]
	v_mfma_f32_16x16x32_bf16 v[18:21], v[26:29], v[172:175], v[86:89]
	v_mfma_f32_16x16x32_bf16 v[18:21], v[38:41], v[176:179], v[18:21]
	v_mfma_f32_16x16x32_bf16 v[22:25], v[50:53], v[172:175], v[82:85]
	v_mfma_f32_16x16x32_bf16 v[22:25], v[54:57], v[176:179], v[22:25]
	s_setprio 0
	s_barrier

; #define PG8_STAGE(bufoff, gbase, voff) do { _Pragma("unroll") for (int _i = 0; _i < 2; ++_i) \
;         __builtin_amdgcn_global_load_lds((const unsigned*)((const char*)(gbase) + (voff)[_i]), (PG8_LAS unsigned*)(lds + (bufoff) + ldsw + _i * 8192), 16, 0, 0); } while (0)
; #define PG8_LDA(dst, b, h) do { _Pragma("unroll") for (int m = 0; m < 4; ++m) _Pragma("unroll") for (int k = 0; k < 2; ++k) dst[m][k] = *(const PG8_LAS bf16x8*)(lds + PG8_SA(b, h) + aoff + m * 2048 + k * 1024); } while (0)
; #define PG8_LDB(dst, b, h) do { _Pragma("unroll") for (int n = 0; n < 2; ++n) _Pragma("unroll") for (int k = 0; k < 2; ++k) dst[n][k] = *(const PG8_LAS bf16x8*)(lds + PG8_SB(b, h) + boff + n * 2048 + k * 1024); } while (0)
; #define PG8_MMA(ai, bj, At, Bt) do { __builtin_amdgcn_s_setprio(1); _Pragma("unroll") for (int m = 0; m < 4; ++m) _Pragma("unroll") for (int n = 0; n < 2; ++n) _Pragma("unroll") for (int k = 0; k < 2; ++k) \
;         acc[ai][bj][m][n] = __builtin_amdgcn_mfma_f32_16x16x32_bf16(Bt[n][k], At[m][k], acc[ai][bj][m][n], 0, 0, 0); __builtin_amdgcn_s_setprio(0); } while (0)
; #define PG8_WAIT_V(n) asm volatile("s_waitcnt vmcnt(" #n ")" ::: "memory")
; #define PG8_WAIT_L(n) asm volatile("s_waitcnt lgkmcnt(" #n ")" ::: "memory")
; #define PG8_BAR __builtin_amdgcn_s_barrier()
; #define PG8_SCHED __builtin_amdgcn_sched_barrier(0)
;     ...
;             const bool last = (t == nt - 2);
;             const char* a1 = cA + (ptrdiff_t)(t + 1) * kstepA;
;             const char* a2 = last ? nA : cA + (ptrdiff_t)(t + 2) * kstepA; const char* b2 = last ? nB : cB + (ptrdiff_t)(t + 2) * kstep;
;             const char* a3 = a2 + kstepA; const char* b3 = b2 + kstep;
;             if (last && has_next) S.a_ready(nxt);
;             if constexpr (SP2) {
;             PG8_LDB(B0, 0, 0); PG8_LDB(B1, 0, 1); PG8_SCHED; PG8_LDA(At, 0, 0); PG8_STAGE(PG8_SA(1, 1), a1 + hstepA, voffA);
;             PG8_WAIT_V(8); PG8_WAIT_L(0); PG8_BAR; PG8_MMA(0, 0, At, B0); PG8_MMA(0, 1, At, B1); PG8_BAR; PG8_SCHED;
;             PG8_LDA(At, 0, 1); PG8_STAGE(PG8_SB(0, 0), b2, voffB); PG8_STAGE(PG8_SB(0, 1), b2 + hstepB, voffB); PG8_STAGE(PG8_SA(0, 0), a2, voffA);
;             PG8_WAIT_V(8); PG8_WAIT_L(0); PG8_BAR; PG8_MMA(1, 0, At, B0); PG8_MMA(1, 1, At, B1); PG8_BAR; PG8_SCHED;
.LBB0_1128:
	s_add_i32 s65, 0, 0x10000
	v_add_u32_e32 v0, s65, v242
	s_add_i32 s66, 0, 0x14000
	s_waitcnt lgkmcnt(0)
	ds_read_b128 v[130:133], v0
	ds_read_b128 v[134:137], v0 offset:1024
	ds_read_b128 v[138:141], v0 offset:2048
	ds_read_b128 v[142:145], v0 offset:3072
	v_add_u32_e32 v0, s66, v242
	ds_read_b128 v[146:149], v0
	ds_read_b128 v[150:153], v0 offset:1024
	ds_read_b128 v[154:157], v0 offset:2048
	ds_read_b128 v[158:161], v0 offset:3072
	ds_read_b128 v[162:165], v243
	ds_read_b128 v[166:169], v243 offset:1024
	ds_read_b128 v[170:173], v243 offset:2048
	ds_read_b128 v[174:177], v243 offset:3072
	ds_read_b128 v[178:181], v243 offset:4096
	ds_read_b128 v[182:185], v243 offset:5120
	ds_read_b128 v[198:201], v243 offset:6144
	ds_read_b128 v[202:205], v243 offset:7168
	s_add_i32 m0, s51, 0xc000
	s_add_u32 s36, s34, 0x4000
	s_addc_u32 s37, s35, 0
	s_cmp_eq_u32 s57, 28
	s_cselect_b32 s86, s29, s36
	s_cselect_b32 s87, s23, s37
	s_cselect_b32 s46, s31, s44
	s_cselect_b32 s47, s21, s56
	s_add_u32 s36, s86, 0x8000
	s_addc_u32 s37, s87, 0
	global_load_lds_dwordx4 v194, s[34:35]
	s_add_i32 m0, s51, 0xe000
	s_nop 0
	global_load_lds_dwordx4 v196, s[34:35]
	s_waitcnt vmcnt(8)
	s_waitcnt lgkmcnt(0)
	s_barrier
	s_setprio 1
	s_waitcnt lgkmcnt(0)
	v_mfma_f32_16x16x32_bf16 v[126:129], v[130:133], v[162:165], v[126:129]
	v_mfma_f32_16x16x32_bf16 v[126:129], v[134:137], v[166:169], v[126:129]
	v_mfma_f32_16x16x32_bf16 v[122:125], v[142:145], v[166:169], v[122:125]
	v_mfma_f32_16x16x32_bf16 v[122:125], v[138:141], v[162:165], v[122:125]
	v_mfma_f32_16x16x32_bf16 v[106:109], v[138:141], v[170:173], v[106:109]
	v_mfma_f32_16x16x32_bf16 v[106:109], v[142:145], v[174:177], v[106:109]
	v_mfma_f32_16x16x32_bf16 v[110:113], v[134:137], v[174:177], v[110:113]
	v_mfma_f32_16x16x32_bf16 v[110:113], v[130:133], v[170:173], v[110:113]
	v_mfma_f32_16x16x32_bf16 v[94:97], v[130:133], v[178:181], v[94:97]
	v_mfma_f32_16x16x32_bf16 v[94:97], v[134:137], v[182:185], v[94:97]
	v_mfma_f32_16x16x32_bf16 v[90:93], v[142:145], v[182:185], v[90:93]
	v_mfma_f32_16x16x32_bf16 v[90:93], v[138:141], v[178:181], v[90:93]
	v_mfma_f32_16x16x32_bf16 v[74:77], v[138:141], v[198:201], v[74:77]
	v_mfma_f32_16x16x32_bf16 v[74:77], v[142:145], v[202:205], v[74:77]
	v_mfma_f32_16x16x32_bf16 v[78:81], v[134:137], v[202:205], v[78:81]
	v_mfma_f32_16x16x32_bf16 v[78:81], v[130:133], v[198:201], v[78:81]
	s_setprio 0
	s_setprio 1
	v_mfma_f32_16x16x32_bf16 v[118:121], v[146:149], v[162:165], v[118:121]
	v_mfma_f32_16x16x32_bf16 v[118:121], v[150:153], v[166:169], v[118:121]
	v_mfma_f32_16x16x32_bf16 v[114:117], v[158:161], v[166:169], v[114:117]
	v_mfma_f32_16x16x32_bf16 v[114:117], v[154:157], v[162:165], v[114:117]
	v_mfma_f32_16x16x32_bf16 v[98:101], v[154:157], v[170:173], v[98:101]
	v_mfma_f32_16x16x32_bf16 v[98:101], v[158:161], v[174:177], v[98:101]
	v_mfma_f32_16x16x32_bf16 v[102:105], v[150:153], v[174:177], v[102:105]
	v_mfma_f32_16x16x32_bf16 v[102:105], v[146:149], v[170:173], v[102:105]
	v_mfma_f32_16x16x32_bf16 v[86:89], v[146:149], v[178:181], v[86:89]
	v_mfma_f32_16x16x32_bf16 v[86:89], v[150:153], v[182:185], v[86:89]
	v_mfma_f32_16x16x32_bf16 v[82:85], v[158:161], v[182:185], v[82:85]
	v_mfma_f32_16x16x32_bf16 v[82:85], v[154:157], v[178:181], v[82:85]
	v_mfma_f32_16x16x32_bf16 v[66:69], v[154:157], v[198:201], v[66:69]
	v_mfma_f32_16x16x32_bf16 v[66:69], v[158:161], v[202:205], v[66:69]
	v_mfma_f32_16x16x32_bf16 v[70:73], v[150:153], v[202:205], v[70:73]
	v_mfma_f32_16x16x32_bf16 v[70:73], v[146:149], v[198:201], v[70:73]
	s_setprio 0
	s_barrier
	s_add_i32 s65, s65, s49
	s_mov_b32 m0, s65
	ds_read_b128 v[162:165], v243 offset:16384
	ds_read_b128 v[166:169], v243 offset:17408
	ds_read_b128 v[170:173], v243 offset:18432
	ds_read_b128 v[174:177], v243 offset:19456
	ds_read_b128 v[178:181], v243 offset:20480
	ds_read_b128 v[182:185], v243 offset:21504
	ds_read_b128 v[198:201], v243 offset:22528
	ds_read_b128 v[202:205], v243 offset:23552
	global_load_lds_dwordx4 v188, s[46:47]
	s_add_i32 m0, s65, 0x2000
	s_add_u32 s90, s46, 0x4000
	s_addc_u32 s91, s47, 0
	s_add_i32 s65, s66, s49
	global_load_lds_dwordx4 v192, s[46:47]
	s_mov_b32 m0, s65
	s_nop 0
	global_load_lds_dwordx4 v188, s[90:91]
	s_add_i32 m0, s65, 0x2000
	s_nop 0
	global_load_lds_dwordx4 v192, s[90:91]
	s_mov_b32 m0, s51
	s_nop 0
	global_load_lds_dwordx4 v186, s[86:87]
	s_mov_b32 m0, s54
	s_nop 0
	global_load_lds_dwordx4 v190, s[86:87]
	s_waitcnt vmcnt(8)
	s_waitcnt lgkmcnt(0)
	s_barrier
	s_setprio 1
	s_waitcnt lgkmcnt(0)
	v_mfma_f32_16x16x32_bf16 v[62:65], v[130:133], v[162:165], v[62:65]
	v_mfma_f32_16x16x32_bf16 v[62:65], v[134:137], v[166:169], v[62:65]
	v_mfma_f32_16x16x32_bf16 v[58:61], v[142:145], v[166:169], v[58:61]
	v_mfma_f32_16x16x32_bf16 v[58:61], v[138:141], v[162:165], v[58:61]
	v_mfma_f32_16x16x32_bf16 v[42:45], v[138:141], v[170:173], v[42:45]
	v_mfma_f32_16x16x32_bf16 v[42:45], v[142:145], v[174:177], v[42:45]
	v_mfma_f32_16x16x32_bf16 v[46:49], v[134:137], v[174:177], v[46:49]
	v_mfma_f32_16x16x32_bf16 v[46:49], v[130:133], v[170:173], v[46:49]
	v_mfma_f32_16x16x32_bf16 v[30:33], v[130:133], v[178:181], v[30:33]
	v_mfma_f32_16x16x32_bf16 v[30:33], v[134:137], v[182:185], v[30:33]
	v_mfma_f32_16x16x32_bf16 v[26:29], v[142:145], v[182:185], v[26:29]
	v_mfma_f32_16x16x32_bf16 v[26:29], v[138:141], v[178:181], v[26:29]
	v_mfma_f32_16x16x32_bf16 v[10:13], v[138:141], v[198:201], v[10:13]
	v_mfma_f32_16x16x32_bf16 v[10:13], v[142:145], v[202:205], v[10:13]
	v_mfma_f32_16x16x32_bf16 v[14:17], v[134:137], v[202:205], v[14:17]
	v_mfma_f32_16x16x32_bf16 v[14:17], v[130:133], v[198:201], v[14:17]
	s_setprio 0
	s_setprio 1
	v_mfma_f32_16x16x32_bf16 v[54:57], v[146:149], v[162:165], v[54:57]
	v_mfma_f32_16x16x32_bf16 v[54:57], v[150:153], v[166:169], v[54:57]
	v_mfma_f32_16x16x32_bf16 v[50:53], v[158:161], v[166:169], v[50:53]
	v_mfma_f32_16x16x32_bf16 v[50:53], v[154:157], v[162:165], v[50:53]
	v_mfma_f32_16x16x32_bf16 v[34:37], v[154:157], v[170:173], v[34:37]
	v_mfma_f32_16x16x32_bf16 v[34:37], v[158:161], v[174:177], v[34:37]
	v_mfma_f32_16x16x32_bf16 v[38:41], v[150:153], v[174:177], v[38:41]
	v_mfma_f32_16x16x32_bf16 v[38:41], v[146:149], v[170:173], v[38:41]
	v_mfma_f32_16x16x32_bf16 v[22:25], v[146:149], v[178:181], v[22:25]
	v_mfma_f32_16x16x32_bf16 v[22:25], v[150:153], v[182:185], v[22:25]
	v_mfma_f32_16x16x32_bf16 v[18:21], v[158:161], v[182:185], v[18:21]
	v_mfma_f32_16x16x32_bf16 v[18:21], v[154:157], v[178:181], v[18:21]
	v_mfma_f32_16x16x32_bf16 v[2:5], v[154:157], v[198:201], v[2:5]
	v_mfma_f32_16x16x32_bf16 v[2:5], v[158:161], v[202:205], v[2:5]
	v_mfma_f32_16x16x32_bf16 v[6:9], v[150:153], v[202:205], v[6:9]
	v_mfma_f32_16x16x32_bf16 v[6:9], v[146:149], v[198:201], v[6:9]
	s_setprio 0
	s_barrier

; #define PG8_STAGE(bufoff, gbase, voff) do { _Pragma("unroll") for (int _i = 0; _i < 2; ++_i) \
;         __builtin_amdgcn_global_load_lds((const unsigned*)((const char*)(gbase) + (voff)[_i]), (PG8_LAS unsigned*)(lds + (bufoff) + ldsw + _i * 8192), 16, 0, 0); } while (0)
; #define PG8_LDA(dst, b, h) do { _Pragma("unroll") for (int m = 0; m < 4; ++m) _Pragma("unroll") for (int k = 0; k < 2; ++k) dst[m][k] = *(const PG8_LAS bf16x8*)(lds + PG8_SA(b, h) + aoff + m * 2048 + k * 1024); } while (0)
; #define PG8_LDB(dst, b, h) do { _Pragma("unroll") for (int n = 0; n < 2; ++n) _Pragma("unroll") for (int k = 0; k < 2; ++k) dst[n][k] = *(const PG8_LAS bf16x8*)(lds + PG8_SB(b, h) + boff + n * 2048 + k * 1024); } while (0)
; #define PG8_MMA(ai, bj, At, Bt) do { __builtin_amdgcn_s_setprio(1); _Pragma("unroll") for (int m = 0; m < 4; ++m) _Pragma("unroll") for (int n = 0; n < 2; ++n) _Pragma("unroll") for (int k = 0; k < 2; ++k) \
;         acc[ai][bj][m][n] = __builtin_amdgcn_mfma_f32_16x16x32_bf16(Bt[n][k], At[m][k], acc[ai][bj][m][n], 0, 0, 0); __builtin_amdgcn_s_setprio(0); } while (0)
; #define PG8_WAIT_V(n) asm volatile("s_waitcnt vmcnt(" #n ")" ::: "memory")
; #define PG8_WAIT_L(n) asm volatile("s_waitcnt lgkmcnt(" #n ")" ::: "memory")
; #define PG8_BAR __builtin_amdgcn_s_barrier()
; #define PG8_SCHED __builtin_amdgcn_sched_barrier(0)
;     ...
;             const bool last = (t == nt - 2);
;             const char* a1 = cA + (ptrdiff_t)(t + 1) * kstepA;
;             const char* a2 = last ? nA : cA + (ptrdiff_t)(t + 2) * kstepA; const char* b2 = last ? nB : cB + (ptrdiff_t)(t + 2) * kstep;
;             const char* a3 = a2 + kstepA; const char* b3 = b2 + kstep;
;             if (last && has_next) S.a_ready(nxt);
;             if constexpr (SP2) {
;             PG8_LDB(B0, 0, 0); PG8_LDB(B1, 0, 1); PG8_SCHED; PG8_LDA(At, 0, 0); PG8_STAGE(PG8_SA(1, 1), a1 + hstepA, voffA);
;             PG8_WAIT_V(8); PG8_WAIT_L(0); PG8_BAR; PG8_MMA(0, 0, At, B0); PG8_MMA(0, 1, At, B1); PG8_BAR; PG8_SCHED;
;             PG8_LDA(At, 0, 1); PG8_STAGE(PG8_SB(0, 0), b2, voffB); PG8_STAGE(PG8_SB(0, 1), b2 + hstepB, voffB); PG8_STAGE(PG8_SA(0, 0), a2, voffA);
;             PG8_WAIT_V(8); PG8_WAIT_L(0); PG8_BAR; PG8_MMA(1, 0, At, B0); PG8_MMA(1, 1, At, B1); PG8_BAR; PG8_SCHED;
.LBB0_1256:
	s_add_i32 s96, 0, 0x10000
	v_add_u32_e32 v0, s96, v192
	s_add_i32 s97, 0, 0x14000
	ds_read_b128 v[130:133], v0
	ds_read_b128 v[134:137], v0 offset:1024
	ds_read_b128 v[138:141], v0 offset:2048
	ds_read_b128 v[142:145], v0 offset:3072
	v_add_u32_e32 v0, s97, v192
	ds_read_b128 v[146:149], v0
	ds_read_b128 v[150:153], v0 offset:1024
	ds_read_b128 v[154:157], v0 offset:2048
	ds_read_b128 v[170:173], v0 offset:3072
	ds_read_b128 v[174:177], v193
	ds_read_b128 v[178:181], v193 offset:1024
	ds_read_b128 v[182:185], v193 offset:2048
	ds_read_b128 v[186:189], v193 offset:3072
	ds_read_b128 v[194:197], v193 offset:4096
	ds_read_b128 v[198:201], v193 offset:5120
	ds_read_b128 v[202:205], v193 offset:6144
	ds_read_b128 v[206:209], v193 offset:7168
	s_add_i32 m0, s48, 0xc000
	s_add_u32 s36, s34, 0x10000
	s_addc_u32 s37, s35, 0
	s_cmp_eq_u32 s66, 28
	s_cselect_b32 s88, s57, s36
	s_cselect_b32 s89, s27, s37
	s_cselect_b32 s86, vcc_lo, vcc_hi
	s_cselect_b32 s87, s25, s65
	s_add_u32 s46, s88, 0x8000
	s_addc_u32 s47, s89, 0
	global_load_lds_dwordx4 v166, s[34:35]
	s_add_i32 m0, s48, 0xe000
	s_nop 0
	global_load_lds_dwordx4 v168, s[34:35]
	s_waitcnt vmcnt(8)
	s_waitcnt lgkmcnt(0)
	s_barrier
	s_setprio 1
	s_waitcnt lgkmcnt(0)
	v_mfma_f32_16x16x32_bf16 v[126:129], v[130:133], v[174:177], v[126:129]
	v_mfma_f32_16x16x32_bf16 v[126:129], v[134:137], v[178:181], v[126:129]
	v_mfma_f32_16x16x32_bf16 v[122:125], v[142:145], v[178:181], v[122:125]
	v_mfma_f32_16x16x32_bf16 v[122:125], v[138:141], v[174:177], v[122:125]
	v_mfma_f32_16x16x32_bf16 v[114:117], v[138:141], v[182:185], v[114:117]
	v_mfma_f32_16x16x32_bf16 v[114:117], v[142:145], v[186:189], v[114:117]
	v_mfma_f32_16x16x32_bf16 v[118:121], v[134:137], v[186:189], v[118:121]
	v_mfma_f32_16x16x32_bf16 v[118:121], v[130:133], v[182:185], v[118:121]
	v_mfma_f32_16x16x32_bf16 v[110:113], v[130:133], v[194:197], v[110:113]
	v_mfma_f32_16x16x32_bf16 v[110:113], v[134:137], v[198:201], v[110:113]
	v_mfma_f32_16x16x32_bf16 v[106:109], v[142:145], v[198:201], v[106:109]
	v_mfma_f32_16x16x32_bf16 v[106:109], v[138:141], v[194:197], v[106:109]
	v_mfma_f32_16x16x32_bf16 v[98:101], v[138:141], v[202:205], v[98:101]
	v_mfma_f32_16x16x32_bf16 v[98:101], v[142:145], v[206:209], v[98:101]
	v_mfma_f32_16x16x32_bf16 v[102:105], v[134:137], v[206:209], v[102:105]
	v_mfma_f32_16x16x32_bf16 v[102:105], v[130:133], v[202:205], v[102:105]
	s_setprio 0
	s_setprio 1
	v_mfma_f32_16x16x32_bf16 v[30:33], v[146:149], v[174:177], v[30:33]
	v_mfma_f32_16x16x32_bf16 v[30:33], v[150:153], v[178:181], v[30:33]
	v_mfma_f32_16x16x32_bf16 v[46:49], v[170:173], v[178:181], v[46:49]
	v_mfma_f32_16x16x32_bf16 v[46:49], v[154:157], v[174:177], v[46:49]
	v_mfma_f32_16x16x32_bf16 v[34:37], v[154:157], v[182:185], v[34:37]
	v_mfma_f32_16x16x32_bf16 v[34:37], v[170:173], v[186:189], v[34:37]
	v_mfma_f32_16x16x32_bf16 v[26:29], v[150:153], v[186:189], v[26:29]
	v_mfma_f32_16x16x32_bf16 v[26:29], v[146:149], v[182:185], v[26:29]
	v_mfma_f32_16x16x32_bf16 v[94:97], v[146:149], v[194:197], v[94:97]
	v_mfma_f32_16x16x32_bf16 v[94:97], v[150:153], v[198:201], v[94:97]
	v_mfma_f32_16x16x32_bf16 v[90:93], v[170:173], v[198:201], v[90:93]
	v_mfma_f32_16x16x32_bf16 v[90:93], v[154:157], v[194:197], v[90:93]
	v_mfma_f32_16x16x32_bf16 v[82:85], v[154:157], v[202:205], v[82:85]
	v_mfma_f32_16x16x32_bf16 v[82:85], v[170:173], v[206:209], v[82:85]
	v_mfma_f32_16x16x32_bf16 v[86:89], v[150:153], v[206:209], v[86:89]
	v_mfma_f32_16x16x32_bf16 v[86:89], v[146:149], v[202:205], v[86:89]
	s_setprio 0
	s_barrier
	s_add_i32 s34, s96, s44
	s_mov_b32 m0, s34
	ds_read_b128 v[174:177], v193 offset:16384
	ds_read_b128 v[178:181], v193 offset:17408
	ds_read_b128 v[182:185], v193 offset:18432
	ds_read_b128 v[186:189], v193 offset:19456
	ds_read_b128 v[194:197], v193 offset:20480
	ds_read_b128 v[198:201], v193 offset:21504
	ds_read_b128 v[202:205], v193 offset:22528
	ds_read_b128 v[206:209], v193 offset:23552
	global_load_lds_dwordx4 v162, s[86:87]
	s_add_i32 m0, s34, 0x2000
	s_add_u32 s34, s86, 0x4000
	s_addc_u32 s35, s87, 0
	s_add_i32 s96, s97, s44
	global_load_lds_dwordx4 v158, s[86:87]
	s_mov_b32 m0, s96
	v_lshl_add_u64 v[210:211], s[88:89], 0, v[160:161]
	global_load_lds_dwordx4 v162, s[34:35]
	s_add_i32 m0, s96, 0x2000
	s_nop 0
	global_load_lds_dwordx4 v158, s[34:35]
	v_lshl_add_u64 v[190:191], s[88:89], 0, v[164:165]
	s_mov_b32 m0, s48
	s_nop 0
	global_load_lds_dwordx4 v[190:191], off
	s_mov_b32 m0, s49
	s_nop 0
	global_load_lds_dwordx4 v[210:211], off
	s_waitcnt vmcnt(8)
	s_waitcnt lgkmcnt(0)
	s_barrier
	s_setprio 1
	s_waitcnt lgkmcnt(0)
	v_mfma_f32_16x16x32_bf16 v[78:81], v[130:133], v[174:177], v[78:81]
	v_mfma_f32_16x16x32_bf16 v[78:81], v[134:137], v[178:181], v[78:81]
	v_mfma_f32_16x16x32_bf16 v[74:77], v[142:145], v[178:181], v[74:77]
	v_mfma_f32_16x16x32_bf16 v[74:77], v[138:141], v[174:177], v[74:77]
	v_mfma_f32_16x16x32_bf16 v[66:69], v[138:141], v[182:185], v[66:69]
	v_mfma_f32_16x16x32_bf16 v[66:69], v[142:145], v[186:189], v[66:69]
	v_mfma_f32_16x16x32_bf16 v[70:73], v[134:137], v[186:189], v[70:73]
	v_mfma_f32_16x16x32_bf16 v[70:73], v[130:133], v[182:185], v[70:73]
	v_mfma_f32_16x16x32_bf16 v[42:45], v[130:133], v[194:197], v[42:45]
	v_mfma_f32_16x16x32_bf16 v[42:45], v[134:137], v[198:201], v[42:45]
	v_mfma_f32_16x16x32_bf16 v[6:9], v[142:145], v[198:201], v[6:9]
	v_mfma_f32_16x16x32_bf16 v[6:9], v[138:141], v[194:197], v[6:9]
	v_mfma_f32_16x16x32_bf16 v[2:5], v[138:141], v[202:205], v[2:5]
	v_mfma_f32_16x16x32_bf16 v[2:5], v[142:145], v[206:209], v[2:5]
	v_mfma_f32_16x16x32_bf16 v[38:41], v[134:137], v[206:209], v[38:41]
	v_mfma_f32_16x16x32_bf16 v[38:41], v[130:133], v[202:205], v[38:41]
	s_setprio 0
	s_setprio 1
	v_mfma_f32_16x16x32_bf16 v[62:65], v[146:149], v[174:177], v[62:65]
	v_mfma_f32_16x16x32_bf16 v[62:65], v[150:153], v[178:181], v[62:65]
	v_mfma_f32_16x16x32_bf16 v[58:61], v[170:173], v[178:181], v[58:61]
	v_mfma_f32_16x16x32_bf16 v[58:61], v[154:157], v[174:177], v[58:61]
	v_mfma_f32_16x16x32_bf16 v[50:53], v[154:157], v[182:185], v[50:53]
	v_mfma_f32_16x16x32_bf16 v[50:53], v[170:173], v[186:189], v[50:53]
	v_mfma_f32_16x16x32_bf16 v[54:57], v[150:153], v[186:189], v[54:57]
	v_mfma_f32_16x16x32_bf16 v[54:57], v[146:149], v[182:185], v[54:57]
	v_mfma_f32_16x16x32_bf16 v[22:25], v[146:149], v[194:197], v[22:25]
	v_mfma_f32_16x16x32_bf16 v[22:25], v[150:153], v[198:201], v[22:25]
	v_mfma_f32_16x16x32_bf16 v[18:21], v[170:173], v[198:201], v[18:21]
	v_mfma_f32_16x16x32_bf16 v[18:21], v[154:157], v[194:197], v[18:21]
	v_mfma_f32_16x16x32_bf16 v[10:13], v[154:157], v[202:205], v[10:13]
	v_mfma_f32_16x16x32_bf16 v[10:13], v[170:173], v[206:209], v[10:13]
	v_mfma_f32_16x16x32_bf16 v[14:17], v[150:153], v[206:209], v[14:17]
	v_mfma_f32_16x16x32_bf16 v[14:17], v[146:149], v[202:205], v[14:17]
	s_setprio 0
	s_barrier

; #define PG8_STAGE(bufoff, gbase, voff) do { _Pragma("unroll") for (int _i = 0; _i < 2; ++_i) \
;         __builtin_amdgcn_global_load_lds((const unsigned*)((const char*)(gbase) + (voff)[_i]), (PG8_LAS unsigned*)(lds + (bufoff) + ldsw + _i * 8192), 16, 0, 0); } while (0)
; #define PG8_LDA(dst, b, h) do { _Pragma("unroll") for (int m = 0; m < 4; ++m) _Pragma("unroll") for (int k = 0; k < 2; ++k) dst[m][k] = *(const PG8_LAS bf16x8*)(lds + PG8_SA(b, h) + aoff + m * 2048 + k * 1024); } while (0)
; #define PG8_LDB(dst, b, h) do { _Pragma("unroll") for (int n = 0; n < 2; ++n) _Pragma("unroll") for (int k = 0; k < 2; ++k) dst[n][k] = *(const PG8_LAS bf16x8*)(lds + PG8_SB(b, h) + boff + n * 2048 + k * 1024); } while (0)
; #define PG8_MMA(ai, bj, At, Bt) do { __builtin_amdgcn_s_setprio(1); _Pragma("unroll") for (int m = 0; m < 4; ++m) _Pragma("unroll") for (int n = 0; n < 2; ++n) _Pragma("unroll") for (int k = 0; k < 2; ++k) \
;         acc[ai][bj][m][n] = __builtin_amdgcn_mfma_f32_16x16x32_bf16(Bt[n][k], At[m][k], acc[ai][bj][m][n], 0, 0, 0); __builtin_amdgcn_s_setprio(0); } while (0)
; #define PG8_WAIT_V(n) asm volatile("s_waitcnt vmcnt(" #n ")" ::: "memory")
; #define PG8_WAIT_L(n) asm volatile("s_waitcnt lgkmcnt(" #n ")" ::: "memory")
; #define PG8_BAR __builtin_amdgcn_s_barrier()
; #define PG8_SCHED __builtin_amdgcn_sched_barrier(0)
;     ...
;             const char* a1 = cA + (ptrdiff_t)(t + 1) * kstepA;
;             const char* a2 = last ? nA : cA + (ptrdiff_t)(t + 2) * kstepA; const char* b2 = last ? nB : cB + (ptrdiff_t)(t + 2) * kstep;
;             const char* a3 = a2 + kstepA; const char* b3 = b2 + kstep;
;             if (last && has_next) S.a_ready(nxt);
;             if constexpr (SP2) {
;             PG8_LDB(B0, 0, 0); PG8_LDB(B1, 0, 1); PG8_SCHED; PG8_LDA(At, 0, 0); PG8_STAGE(PG8_SA(1, 1), a1 + hstepA, voffA);
;             PG8_WAIT_V(8); PG8_WAIT_L(0); PG8_BAR; PG8_MMA(0, 0, At, B0); PG8_MMA(0, 1, At, B1); PG8_BAR; PG8_SCHED;
;             PG8_LDA(At, 0, 1); PG8_STAGE(PG8_SB(0, 0), b2, voffB); PG8_STAGE(PG8_SB(0, 1), b2 + hstepB, voffB); PG8_STAGE(PG8_SA(0, 0), a2, voffA);
;             PG8_WAIT_V(8); PG8_WAIT_L(0); PG8_BAR; PG8_MMA(1, 0, At, B0); PG8_MMA(1, 1, At, B1); PG8_BAR; PG8_SCHED;
.LBB0_1444:
	s_add_i32 m0, s46, 0xc000
	s_or_b32 s44, s56, 1
	s_lshl_b64 s[34:35], s[44:45], 15
	s_sub_u32 s34, 0, s34
	s_subb_u32 s35, 0, s35
	s_add_u32 s44, s28, s34
	s_addc_u32 s65, s29, s35
	s_add_u32 s34, s30, 0xffff8000
	s_addc_u32 s35, s31, -1
	s_add_u32 s88, s44, 0x4000
	s_addc_u32 s89, s65, 0
	global_load_lds_dwordx4 v194, s[88:89]
	s_add_i32 m0, s46, 0xe000
	s_nop 0
	global_load_lds_dwordx4 v198, s[88:89]
	s_waitcnt vmcnt(8)
	s_waitcnt lgkmcnt(0)
	s_barrier
	s_setprio 1
	s_waitcnt lgkmcnt(0)
	v_mfma_f32_16x16x32_bf16 v[126:129], v[130:133], v[162:165], v[126:129]
	v_mfma_f32_16x16x32_bf16 v[126:129], v[134:137], v[166:169], v[126:129]
	v_mfma_f32_16x16x32_bf16 v[122:125], v[142:145], v[166:169], v[122:125]
	v_mfma_f32_16x16x32_bf16 v[122:125], v[138:141], v[162:165], v[122:125]
	v_mfma_f32_16x16x32_bf16 v[106:109], v[138:141], v[170:173], v[106:109]
	v_mfma_f32_16x16x32_bf16 v[106:109], v[142:145], v[174:177], v[106:109]
	v_mfma_f32_16x16x32_bf16 v[110:113], v[134:137], v[174:177], v[110:113]
	v_mfma_f32_16x16x32_bf16 v[110:113], v[130:133], v[170:173], v[110:113]
	v_mfma_f32_16x16x32_bf16 v[94:97], v[130:133], v[178:181], v[94:97]
	v_mfma_f32_16x16x32_bf16 v[94:97], v[134:137], v[182:185], v[94:97]
	v_mfma_f32_16x16x32_bf16 v[90:93], v[142:145], v[182:185], v[90:93]
	v_mfma_f32_16x16x32_bf16 v[90:93], v[138:141], v[178:181], v[90:93]
	v_mfma_f32_16x16x32_bf16 v[74:77], v[138:141], v[186:189], v[74:77]
	v_mfma_f32_16x16x32_bf16 v[74:77], v[142:145], v[190:193], v[74:77]
	v_mfma_f32_16x16x32_bf16 v[78:81], v[134:137], v[190:193], v[78:81]
	v_mfma_f32_16x16x32_bf16 v[78:81], v[130:133], v[186:189], v[78:81]
	s_setprio 0
	s_setprio 1
	v_mfma_f32_16x16x32_bf16 v[118:121], v[146:149], v[162:165], v[118:121]
	v_mfma_f32_16x16x32_bf16 v[118:121], v[150:153], v[166:169], v[118:121]
	v_mfma_f32_16x16x32_bf16 v[114:117], v[158:161], v[166:169], v[114:117]
	v_mfma_f32_16x16x32_bf16 v[114:117], v[154:157], v[162:165], v[114:117]
	v_mfma_f32_16x16x32_bf16 v[98:101], v[154:157], v[170:173], v[98:101]
	v_mfma_f32_16x16x32_bf16 v[98:101], v[158:161], v[174:177], v[98:101]
	v_mfma_f32_16x16x32_bf16 v[102:105], v[150:153], v[174:177], v[102:105]
	v_mfma_f32_16x16x32_bf16 v[102:105], v[146:149], v[170:173], v[102:105]
	v_mfma_f32_16x16x32_bf16 v[86:89], v[146:149], v[178:181], v[86:89]
	v_mfma_f32_16x16x32_bf16 v[86:89], v[150:153], v[182:185], v[86:89]
	v_mfma_f32_16x16x32_bf16 v[82:85], v[158:161], v[182:185], v[82:85]
	v_mfma_f32_16x16x32_bf16 v[82:85], v[154:157], v[178:181], v[82:85]
	v_mfma_f32_16x16x32_bf16 v[66:69], v[154:157], v[186:189], v[66:69]
	v_mfma_f32_16x16x32_bf16 v[66:69], v[158:161], v[190:193], v[66:69]
	v_mfma_f32_16x16x32_bf16 v[70:73], v[150:153], v[190:193], v[70:73]
	v_mfma_f32_16x16x32_bf16 v[70:73], v[146:149], v[186:189], v[70:73]
	s_setprio 0
	s_barrier
	s_add_i32 s44, s66, s41
	s_mov_b32 m0, s44
	ds_read_b128 v[162:165], v231 offset:16384
	ds_read_b128 v[166:169], v231 offset:17408
	ds_read_b128 v[170:173], v231 offset:18432
	ds_read_b128 v[174:177], v231 offset:19456
	ds_read_b128 v[178:181], v231 offset:20480
	ds_read_b128 v[182:185], v231 offset:21504
	ds_read_b128 v[186:189], v231 offset:22528
	ds_read_b128 v[190:193], v231 offset:23552
	global_load_lds_dwordx4 v196, s[8:9]
	s_add_i32 m0, s44, 0x2000
	s_add_u32 s88, s8, 0x4000
	s_addc_u32 s89, s9, 0
	s_add_i32 s44, s90, s41
	global_load_lds_dwordx4 v200, s[8:9]
	s_mov_b32 m0, s44
	s_nop 0
	global_load_lds_dwordx4 v196, s[88:89]
	s_add_i32 m0, s44, 0x2000
	s_nop 0
	global_load_lds_dwordx4 v200, s[88:89]
	s_mov_b32 m0, s46
	s_nop 0
	global_load_lds_dwordx4 v194, s[30:31]
	s_mov_b32 m0, s47
	s_nop 0
	global_load_lds_dwordx4 v198, s[30:31]
	s_waitcnt vmcnt(8)
	s_waitcnt lgkmcnt(0)
	s_barrier
	s_setprio 1
	s_waitcnt lgkmcnt(0)
	v_mfma_f32_16x16x32_bf16 v[62:65], v[130:133], v[162:165], v[62:65]
	v_mfma_f32_16x16x32_bf16 v[62:65], v[134:137], v[166:169], v[62:65]
	v_mfma_f32_16x16x32_bf16 v[58:61], v[142:145], v[166:169], v[58:61]
	v_mfma_f32_16x16x32_bf16 v[58:61], v[138:141], v[162:165], v[58:61]
	v_mfma_f32_16x16x32_bf16 v[42:45], v[138:141], v[170:173], v[42:45]
	v_mfma_f32_16x16x32_bf16 v[42:45], v[142:145], v[174:177], v[42:45]
	v_mfma_f32_16x16x32_bf16 v[46:49], v[134:137], v[174:177], v[46:49]
	v_mfma_f32_16x16x32_bf16 v[46:49], v[130:133], v[170:173], v[46:49]
	v_mfma_f32_16x16x32_bf16 v[30:33], v[130:133], v[178:181], v[30:33]
	v_mfma_f32_16x16x32_bf16 v[30:33], v[134:137], v[182:185], v[30:33]
	v_mfma_f32_16x16x32_bf16 v[26:29], v[142:145], v[182:185], v[26:29]
	v_mfma_f32_16x16x32_bf16 v[26:29], v[138:141], v[178:181], v[26:29]
	v_mfma_f32_16x16x32_bf16 v[10:13], v[138:141], v[186:189], v[10:13]
	v_mfma_f32_16x16x32_bf16 v[10:13], v[142:145], v[190:193], v[10:13]
	v_mfma_f32_16x16x32_bf16 v[14:17], v[134:137], v[190:193], v[14:17]
	v_mfma_f32_16x16x32_bf16 v[14:17], v[130:133], v[186:189], v[14:17]
	s_setprio 0
	s_setprio 1
	v_mfma_f32_16x16x32_bf16 v[54:57], v[146:149], v[162:165], v[54:57]
	v_mfma_f32_16x16x32_bf16 v[54:57], v[150:153], v[166:169], v[54:57]
	v_mfma_f32_16x16x32_bf16 v[50:53], v[158:161], v[166:169], v[50:53]
	v_mfma_f32_16x16x32_bf16 v[50:53], v[154:157], v[162:165], v[50:53]
	v_mfma_f32_16x16x32_bf16 v[34:37], v[154:157], v[170:173], v[34:37]
	v_mfma_f32_16x16x32_bf16 v[34:37], v[158:161], v[174:177], v[34:37]
	v_mfma_f32_16x16x32_bf16 v[38:41], v[150:153], v[174:177], v[38:41]
	v_mfma_f32_16x16x32_bf16 v[38:41], v[146:149], v[170:173], v[38:41]
	v_mfma_f32_16x16x32_bf16 v[22:25], v[146:149], v[178:181], v[22:25]
	v_mfma_f32_16x16x32_bf16 v[22:25], v[150:153], v[182:185], v[22:25]
	v_mfma_f32_16x16x32_bf16 v[18:21], v[158:161], v[182:185], v[18:21]
	v_mfma_f32_16x16x32_bf16 v[18:21], v[154:157], v[178:181], v[18:21]
	v_mfma_f32_16x16x32_bf16 v[2:5], v[154:157], v[186:189], v[2:5]
	v_mfma_f32_16x16x32_bf16 v[2:5], v[158:161], v[190:193], v[2:5]
	v_mfma_f32_16x16x32_bf16 v[6:9], v[150:153], v[190:193], v[6:9]
	v_mfma_f32_16x16x32_bf16 v[6:9], v[146:149], v[186:189], v[6:9]
	s_setprio 0
	s_barrier

; #define PG8_STAGE(bufoff, gbase, voff) do { _Pragma("unroll") for (int _i = 0; _i < 2; ++_i) \
;         __builtin_amdgcn_global_load_lds((const unsigned*)((const char*)(gbase) + (voff)[_i]), (PG8_LAS unsigned*)(lds + (bufoff) + ldsw + _i * 8192), 16, 0, 0); } while (0)
; #define PG8_LDA(dst, b, h) do { _Pragma("unroll") for (int m = 0; m < 4; ++m) _Pragma("unroll") for (int k = 0; k < 2; ++k) dst[m][k] = *(const PG8_LAS bf16x8*)(lds + PG8_SA(b, h) + aoff + m * 2048 + k * 1024); } while (0)
; #define PG8_LDB(dst, b, h) do { _Pragma("unroll") for (int n = 0; n < 2; ++n) _Pragma("unroll") for (int k = 0; k < 2; ++k) dst[n][k] = *(const PG8_LAS bf16x8*)(lds + PG8_SB(b, h) + boff + n * 2048 + k * 1024); } while (0)
; #define PG8_SCHED __builtin_amdgcn_sched_barrier(0)
;     ...
;             PG8_LDB(B0, 0, 0); PG8_LDB(B1, 0, 1); PG8_SCHED; PG8_LDA(At, 0, 0); PG8_STAGE(PG8_SA(1, 1), a1 + hstepA, voffA);
.Ldn_top:
	s_add_i32 s66, 0, 0x10000
	v_add_u32_e32 v0, s66, v230
	s_add_i32 s90, 0, 0x14000
	s_waitcnt lgkmcnt(0)
	ds_read_b128 v[130:133], v0
	ds_read_b128 v[134:137], v0 offset:1024
	ds_read_b128 v[138:141], v0 offset:2048
	ds_read_b128 v[142:145], v0 offset:3072
	v_add_u32_e32 v0, s90, v230
	ds_read_b128 v[146:149], v0
	ds_read_b128 v[150:153], v0 offset:1024
	ds_read_b128 v[154:157], v0 offset:2048
	ds_read_b128 v[158:161], v0 offset:3072
	ds_read_b128 v[162:165], v231
	ds_read_b128 v[166:169], v231 offset:1024
	ds_read_b128 v[170:173], v231 offset:2048
	ds_read_b128 v[174:177], v231 offset:3072
	ds_read_b128 v[178:181], v231 offset:4096
	ds_read_b128 v[182:185], v231 offset:5120
	ds_read_b128 v[186:189], v231 offset:6144
	ds_read_b128 v[190:193], v231 offset:7168
